# mixer phase order swap keyed on blockIdx bit 0 (XCD parity) instead of bit 3
# baseline (speedup 1.0000x reference)
; #define LAS __attribute__((address_space(3)))
; #define LAUNDER() int tp = TID0(); const int tid = tp, lane = tp & 63, wave = __builtin_amdgcn_readfirstlane(tp >> 6); (void)tid; (void)lane; (void)wave
; __global__ void __launch_bounds__(512) fwd_kernel(Args a) {
;     ...
;         if (IN(pb + 2)) {
;             if (EN_B) { LAUNDER(); LAS char* vt = (LAS char*)lds + wave * 16384;
;                 (void)vt; for (int u = blockIdx.x; u < 256; u += G) { mixerB2_unit(u, l, PROJ, YC, a.in[6] + l * 128, a.in[7] + l * 64, KMAX + l * 1024, (LAS char*)lds, tid, wave, lane); } __syncthreads(); }
;             if (EN_S1) { LAUNDER(); __syncthreads();
;                 for (int u = blockIdx.x; u < 256; u += G) ssd_part1_unit(u, PROJ, DT, H, WDT + l * 16384, a.in[11] + l * 8, a.in[8] + l * 5 * 768, a.in[9] + l * 768, a.in[10] + l * 8, STATES, TOT, lds, tid, wave, lane);
;                 __syncthreads(); }
;             if (EN_A) { LAUNDER(); LAS char* vt = (LAS char*)lds + wave * 16384;
;                 for (int u = blockIdx.x; u < 512; u += G) { mixerA1_unit(u, PROJ, YC, LPA, KMAX + l * 1024, vt, wave, lane); } }
;             if (EN_D) { LAUNDER(); LAS char* vt = (LAS char*)lds + wave * 16384;
;                 int hcur = -1; float rmax = 0.f;
;                 for (int u = blockIdx.x; u < 512; u += G) { const int hd = (u >> 4) & 3; if (hd != hcur) { rmax = d_stage_rpb(a.in[14] + l * 4 * 15 * 31, hd, vt, lane); hcur = hd; }
;                     mixerD2_unit(u, PROJ, YC, rmax, KMAX + l * 1024, vt, wave, lane); } }
.Lmx_b:
	s_cmp_eq_u32 s101, 0
	s_cbranch_scc0 .Lmx_b_go
	s_bitcmp1_b32 s66, 0
	s_cbranch_scc0 .Lmx_b_go
	s_mov_b32 s101, 1
	v_readlane_b32 s56, v255, 10
	s_branch .LBB0_356
